# diff attention loop: waves 4-7 delayed by s_sleep 4 at the head of each tile (stagger against their SIMD partners)
# baseline (speedup 1.0000x reference)
.LBB0_479:
	v_readfirstlane_b32 s0, v208
	s_cmpk_lt_u32 s0, 0x100
	s_cbranch_scc1 .Ldf_nostag
	s_sleep 4
